# combo27 + dn_prep step 3: each 16x16 tile issues its four LDS fragment read pairs together with counted waits
# speedup vs baseline: 1.0147x; 1.0074x over previous
; #define LAS __attribute__((address_space(3)))
; __device__ __forceinline__ void dn_prep(const Params& p, LAS unsigned char* lds) {
;     ...
;                     const LAS float* cw = cw_s + j * 384 + part * 128 + d0;
; #pragma unroll
;                     for (int e4 = 0; e4 < 4; ++e4) { const f32x4 c4 = *(const LAS f32x4*)(cw + e4 * 4);
;                         y[e4 * 4] += xv[e4 * 4] * c4[0]; y[e4 * 4 + 1] += xv[e4 * 4 + 1] * c4[1]; y[e4 * 4 + 2] += xv[e4 * 4 + 2] * c4[2]; y[e4 * 4 + 3] += xv[e4 * 4 + 3] * c4[3]; }
;                     if (j == 3 && whist) {
; #pragma unroll
;                         for (int e4 = 0; e4 < 4; ++e4) *(float4*)(hist_out + c0 + e4 * 4) = make_float4(xv[e4 * 4], xv[e4 * 4 + 1], xv[e4 * 4 + 2], xv[e4 * 4 + 3]);
;                     }
;                 }
;                 float ss = 0.f;
; #pragma unroll
;                 for (int e = 0; e < 16; ++e) { y[e] = valid ? silu_f(y[e]) : 0.f; ss += y[e] * y[e]; }
;                 ss = sum8(ss);
;                 if (part < 2) { const float r = rsqrtf(ss + 1e-6f) * (part == 0 ? 0.08838834764831845f : 1.0f);
; #pragma unroll
;                     for (int e = 0; e < 16; ++e) y[e] *= r; }
;                 u32x4 w0, w1;
;                 w0.x = cvt_pk_bf16(y[0], y[1]); w0.y = cvt_pk_bf16(y[2], y[3]); w0.z = cvt_pk_bf16(y[4], y[5]); w0.w = cvt_pk_bf16(y[6], y[7]);
;                 w1.x = cvt_pk_bf16(y[8], y[9]); w1.y = cvt_pk_bf16(y[10], y[11]); w1.z = cvt_pk_bf16(y[12], y[13]); w1.w = cvt_pk_bf16(y[14], y[15]);
;                 if (part == 0) {
;                     *(LAS u32x4*)(Qs + t * 136 + d0) = w0; *(LAS u32x4*)(Qs + t * 136 + d0 + 8) = w1;
;                     bf16_t* qp = gQS + t * 128 + 32 * (sub >> 1) + 4 * (sub & 1);
;                     *(u32x2*)(qp) = (u32x2){w0.x, w0.y}; *(u32x2*)(qp + 8) = (u32x2){w0.z, w0.w}; *(u32x2*)(qp + 16) = (u32x2){w1.x, w1.y}; *(u32x2*)(qp + 24) = (u32x2){w1.z, w1.w};
;                 } else if (part == 1) {
;                     *(LAS u32x4*)(Ks + t * 136 + d0) = w0; *(LAS u32x4*)(Ks + t * 136 + d0 + 8) = w1;
; #pragma unroll
;                     for (int e = 0; e < 16; ++e) Kts[(d0 + e) * 72 + (t ^ (8 * sub))] = f2bf(y[e]);
;                 } else {
; #pragma unroll
;                     for (int e = 0; e < 16; ++e) Vts[(d0 + e) * 72 + (t ^ (8 * sub))] = f2bf(y[e]);
;                 }
;             }
;         }
;         lds_barrier();
.LBB0_283:
	s_or_b64 exec, exec, s[0:1]
	s_waitcnt lgkmcnt(14)
	v_fma_f32 v13, v13, v45, 0
	s_waitcnt lgkmcnt(12)
	v_fma_f32 v5, v5, v25, 0
	s_waitcnt lgkmcnt(11)
	v_fmac_f32_e32 v13, v53, v85
	s_waitcnt lgkmcnt(8)
	v_fmac_f32_e32 v5, v33, v65
	s_waitcnt lgkmcnt(7)
	v_fmac_f32_e32 v13, v93, v109
	s_waitcnt lgkmcnt(4)
	v_fmac_f32_e32 v5, v69, v61
	s_waitcnt lgkmcnt(3)
	v_fmac_f32_e32 v13, v117, v129
	s_waitcnt lgkmcnt(0)
	v_fmac_f32_e32 v5, v57, v17
	v_mul_f32_e32 v17, 0xbfb8aa3b, v13
	v_fma_f32 v12, v12, v44, 0
	v_exp_f32_e32 v17, v17
	v_fma_f32 v4, v4, v24, 0
	v_fmac_f32_e32 v12, v52, v84
	v_fmac_f32_e32 v4, v32, v64
	v_fmac_f32_e32 v12, v92, v108
	v_fmac_f32_e32 v4, v68, v60
	v_fmac_f32_e32 v12, v116, v128
	v_fmac_f32_e32 v4, v56, v16
	v_mul_f32_e32 v16, 0xbfb8aa3b, v12
	v_add_f32_e32 v17, 1.0, v17
	v_fma_f32 v14, v14, v46, 0
	v_fma_f32 v15, v15, v47, 0
	v_exp_f32_e32 v16, v16
	v_rcp_f32_e32 v17, v17
	v_fma_f32 v6, v6, v26, 0
	v_fmac_f32_e32 v14, v54, v86
	v_fmac_f32_e32 v15, v55, v87
	v_fmac_f32_e32 v6, v34, v66
	v_fmac_f32_e32 v14, v94, v110
	v_fmac_f32_e32 v15, v95, v111
	v_fmac_f32_e32 v6, v70, v62
	v_fmac_f32_e32 v14, v118, v130
	v_fmac_f32_e32 v15, v119, v131
	v_fmac_f32_e32 v6, v58, v18
	v_add_f32_e32 v16, 1.0, v16
	v_mul_f32_e32 v18, 0xbfb8aa3b, v14
	v_mul_f32_e32 v13, v13, v17
	v_mul_f32_e32 v17, 0xbfb8aa3b, v15
	v_fma_f32 v8, v8, v36, 0
	v_rcp_f32_e32 v16, v16
	v_exp_f32_e32 v18, v18
	v_exp_f32_e32 v17, v17
	v_fmac_f32_e32 v8, v48, v80
	v_fmac_f32_e32 v8, v88, v104
	v_fmac_f32_e32 v8, v112, v124
	v_mul_f32_e32 v12, v12, v16
	v_add_f32_e32 v16, 1.0, v18
	v_mul_f32_e32 v18, 0xbfb8aa3b, v8
	v_add_f32_e32 v17, 1.0, v17
	v_fma_f32 v10, v10, v38, 0
	v_exp_f32_e32 v18, v18
	v_rcp_f32_e32 v17, v17
	v_fmac_f32_e32 v10, v50, v82
	v_fmac_f32_e32 v10, v90, v106
	v_fmac_f32_e32 v10, v114, v126
	v_add_f32_e32 v18, 1.0, v18
	v_mul_f32_e32 v15, v15, v17
	v_mul_f32_e32 v17, 0xbfb8aa3b, v10
	v_fma_f32 v9, v9, v37, 0
	v_fma_f32 v11, v11, v39, 0
	v_rcp_f32_e32 v18, v18
	v_exp_f32_e32 v17, v17
	v_fma_f32 v7, v7, v27, 0
	v_fmac_f32_e32 v9, v49, v81
	v_fmac_f32_e32 v11, v51, v83
	v_fmac_f32_e32 v7, v35, v67
	v_fmac_f32_e32 v9, v89, v105
	v_fmac_f32_e32 v11, v91, v107
	v_fmac_f32_e32 v7, v71, v63
	v_fmac_f32_e32 v9, v113, v125
	v_fmac_f32_e32 v11, v115, v127
	v_fmac_f32_e32 v7, v59, v19
	v_mul_f32_e32 v19, 0xbfb8aa3b, v9
	v_mul_f32_e32 v8, v8, v18
	v_mul_f32_e32 v18, 0xbfb8aa3b, v11
	v_add_f32_e32 v17, 1.0, v17
	v_fma_f32 v0, v0, v28, 0
	v_fma_f32 v1, v1, v29, 0
	v_rcp_f32_e32 v16, v16
	v_exp_f32_e32 v19, v19
	v_exp_f32_e32 v18, v18
	v_rcp_f32_e32 v17, v17
	v_fmac_f32_e32 v0, v40, v72
	v_fmac_f32_e32 v1, v41, v73
	v_fmac_f32_e32 v0, v76, v96
	v_fmac_f32_e32 v1, v77, v97
	v_fmac_f32_e32 v0, v100, v20
	v_fmac_f32_e32 v1, v101, v21
	v_mul_f32_e32 v14, v14, v16
	v_add_f32_e32 v16, 1.0, v19
	v_add_f32_e32 v18, 1.0, v18
	v_mul_f32_e32 v19, 0xbfb8aa3b, v0
	v_mul_f32_e32 v10, v10, v17
	v_mul_f32_e32 v17, 0xbfb8aa3b, v1
	v_fma_f32 v2, v2, v30, 0
	v_fma_f32 v3, v3, v31, 0
	v_rcp_f32_e32 v16, v16
	v_rcp_f32_e32 v18, v18
	v_exp_f32_e32 v19, v19
	v_exp_f32_e32 v17, v17
	v_fmac_f32_e32 v2, v42, v74
	v_fmac_f32_e32 v3, v43, v75
	v_fmac_f32_e32 v2, v78, v98
	v_fmac_f32_e32 v3, v79, v99
	v_fmac_f32_e32 v2, v102, v22
	v_fmac_f32_e32 v3, v103, v23
	v_mul_f32_e32 v9, v9, v16
	v_mul_f32_e32 v11, v11, v18
	v_add_f32_e32 v16, 1.0, v19
	v_mul_f32_e32 v18, 0xbfb8aa3b, v2
	v_add_f32_e32 v17, 1.0, v17
	v_mul_f32_e32 v19, 0xbfb8aa3b, v3
	v_exp_f32_e32 v18, v18
	v_rcp_f32_e32 v16, v16
	v_rcp_f32_e32 v17, v17
	v_exp_f32_e32 v19, v19
	v_add_f32_e32 v18, 1.0, v18
	v_mul_f32_e32 v0, v0, v16
	v_mul_f32_e32 v1, v1, v17
	v_add_f32_e32 v16, 1.0, v19
	v_mul_f32_e32 v17, 0xbfb8aa3b, v4
	v_rcp_f32_e32 v18, v18
	v_rcp_f32_e32 v16, v16
	v_exp_f32_e32 v17, v17
	v_mul_u32_u24_e32 v120, 0x900, v139
	v_mul_f32_e32 v2, v2, v18
	v_mul_f32_e32 v18, 0xbfb8aa3b, v5
	v_mul_f32_e32 v3, v3, v16
	v_add_f32_e32 v16, 1.0, v17
	v_exp_f32_e32 v18, v18
	v_rcp_f32_e32 v16, v16
	v_cvt_pk_bf16_f32 v0, v0, s0
	v_cndmask_b32_e64 v0, 0, v0, s[24:25]
	v_add_f32_e32 v17, 1.0, v18
	v_mul_f32_e32 v18, 0xbfb8aa3b, v6
	v_mul_f32_e32 v4, v4, v16
	v_add_u32_e32 v16, v144, v120
	v_exp_f32_e32 v18, v18
	ds_write_b16 v16, v0 offset:54400
	v_cvt_pk_bf16_f32 v0, v1, s0
	v_mul_f32_e32 v19, 0xbfb8aa3b, v7
	v_cndmask_b32_e64 v0, 0, v0, s[24:25]
	v_exp_f32_e32 v19, v19
	ds_write_b16 v16, v0 offset:54544
	v_cvt_pk_bf16_f32 v0, v2, s0
	v_rcp_f32_e32 v17, v17
	v_cndmask_b32_e64 v0, 0, v0, s[24:25]
	v_add_f32_e32 v18, 1.0, v18
	ds_write_b16 v16, v0 offset:54688
	v_cvt_pk_bf16_f32 v0, v3, s0
	v_rcp_f32_e32 v18, v18
	v_cndmask_b32_e64 v0, 0, v0, s[24:25]
	v_add_f32_e32 v19, 1.0, v19
	v_cvt_pk_bf16_f32 v12, v12, s0
	v_cvt_pk_bf16_f32 v8, v8, s0
	ds_write_b16 v16, v0 offset:54832
	v_cvt_pk_bf16_f32 v0, v4, s0
	v_rcp_f32_e32 v19, v19
	v_mul_f32_e32 v5, v5, v17
	v_cndmask_b32_e64 v12, 0, v12, s[24:25]
	v_cndmask_b32_e64 v8, 0, v8, s[24:25]
	v_cndmask_b32_e64 v0, 0, v0, s[24:25]
	ds_write_b16 v16, v12 offset:53248
	v_cvt_pk_bf16_f32 v12, v13, s0
	ds_write_b16 v16, v8 offset:53824
	v_cvt_pk_bf16_f32 v8, v9, s0
	ds_write_b16 v16, v0 offset:54976
	v_cvt_pk_bf16_f32 v0, v5, s0
	v_mul_f32_e32 v6, v6, v18
	v_cndmask_b32_e64 v12, 0, v12, s[24:25]
	v_cndmask_b32_e64 v8, 0, v8, s[24:25]
	v_cndmask_b32_e64 v0, 0, v0, s[24:25]
	ds_write_b16 v16, v12 offset:53392
	v_cvt_pk_bf16_f32 v12, v14, s0
	ds_write_b16 v16, v8 offset:53968
	v_cvt_pk_bf16_f32 v8, v10, s0
	ds_write_b16 v16, v0 offset:55120
	v_cvt_pk_bf16_f32 v0, v6, s0
	v_mul_f32_e32 v7, v7, v19
	v_cndmask_b32_e64 v12, 0, v12, s[24:25]
	v_cndmask_b32_e64 v8, 0, v8, s[24:25]
	v_cndmask_b32_e64 v0, 0, v0, s[24:25]
	ds_write_b16 v16, v12 offset:53536
	v_cvt_pk_bf16_f32 v12, v15, s0
	ds_write_b16 v16, v8 offset:54112
	v_cvt_pk_bf16_f32 v8, v11, s0
	ds_write_b16 v16, v0 offset:55264
	v_cvt_pk_bf16_f32 v0, v7, s0
	v_cndmask_b32_e64 v12, 0, v12, s[24:25]
	v_cndmask_b32_e64 v8, 0, v8, s[24:25]
	v_cndmask_b32_e64 v0, 0, v0, s[24:25]
	ds_write_b16 v16, v12 offset:53680
	ds_write_b16 v16, v8 offset:54256
	ds_write_b16 v16, v0 offset:55408
	s_waitcnt lgkmcnt(0)
	s_barrier
; #define LAS __attribute__((address_space(3)))
; __device__ __forceinline__ f32x4 mfma16(const bf16x8& a, const bf16x8& b, const f32x4& c) { return __builtin_amdgcn_mfma_f32_16x16x32_bf16(a, b, c, 0, 0, 0); }
; __device__ __forceinline__ void dn_prep(const Params& p, LAS unsigned char* lds) {
;     ...
;             const int sel = wid >> 2, ti = wid & 3;
;             int z3; asm volatile("v_mov_b32 %0, 0" : "=v"(z3));
;             const int fr = ((tid + z3) & 15), fq = ((tid + z3) & 63) >> 4;
; #pragma unroll
;             for (int tj = 0; tj < 4; ++tj) {
;                 if (sel == 0) {
;                     if (tj <= ti) {
;                         f32x4 acc = {0.f, 0.f, 0.f, 0.f};
; #pragma unroll
;                         for (int kk = 0; kk < 4; ++kk) { const bf16x8 a = *(const LAS bf16x8*)(Ks + (16 * ti + fr) * 136 + kk * 32 + 8 * fq), bb = *(const LAS bf16x8*)(Ks + (16 * tj + fr) * 136 + kk * 32 + 8 * fq); acc = mfma16(a, bb, acc); }
;                         const int j = 16 * tj + fr; const float Gj = G_s[j];
; #pragma unroll
;                         for (int jj = 0; jj < 4; ++jj) { const int i = 16 * ti + 4 * fq + jj;
;                             As[i * 68 + j] = (i > j) ? beta_s[i] * acc[jj] * __expf(G_s[i] - Gj) : 0.f; }
;                     }
;                 } else {
;                     f32x4 acc = {0.f, 0.f, 0.f, 0.f};
;                     if (tj <= ti) {
; #pragma unroll
;                         for (int kk = 0; kk < 4; ++kk) { const bf16x8 a = *(const LAS bf16x8*)(Ks + (16 * tj + fr) * 136 + kk * 32 + 8 * fq), bb = *(const LAS bf16x8*)(Qs + (16 * ti + fr) * 136 + kk * 32 + 8 * fq); acc = mfma16(a, bb, acc); }
;                     }
;                     const int i = 16 * ti + fr; const float Gi = G_s[i];
;                     float v[4];
; #pragma unroll
;                     for (int jj = 0; jj < 4; ++jj) { const int j = 16 * tj + 4 * fq + jj; v[jj] = (i >= j) ? acc[jj] * __expf(Gi - G_s[j]) : 0.f; }
	v_mov_b32 v0, 0
	s_add_u32 s28, s39, s26
	v_add_u32_e32 v0, v0, v184
	v_and_b32_e32 v12, 15, v0
	v_bfe_u32 v1, v0, 4, 2
	v_or_b32_e32 v6, v12, v155
	s_addc_u32 s29, s36, s27
	v_lshlrev_b32_e32 v0, 4, v1
	v_lshlrev_b32_e32 v132, 7, v6
	v_add_u32_e32 v11, 0, v0
	v_lshlrev_b32_e32 v7, 2, v1
	v_lshl_add_u64 v[2:3], s[28:29], 0, v[132:133]
	v_mov_b32_e32 v1, v133
	v_mad_u32_u24 v9, v6, s10, v11
	v_lshl_add_u32 v8, v6, 2, s37
	v_lshl_add_u64 v[4:5], v[2:3], 0, v[0:1]
	v_mul_u32_u24_e32 v13, 0x110, v12
	s_and_saveexec_b64 s[0:1], s[4:5]
	s_xor_b64 s[24:25], exec, s[0:1]
	s_cbranch_execz .LBB0_293
	v_add_u32_e32 v10, v11, v13
	ds_read_b128 v[0:3], v10 offset:17408
	ds_read_b128 v[14:17], v9
	v_cmp_ge_u32_e32 vcc, v6, v7
	ds_read_b128 v[176:179], v10 offset:17472
	ds_read_b128 v[180:183], v9 offset:64
	ds_read_b128 v[186:189], v10 offset:17536
	ds_read_b128 v[190:193], v9 offset:128
	ds_read_b128 v[194:197], v10 offset:17600
	ds_read_b128 v[198:201], v9 offset:192
	s_waitcnt lgkmcnt(6)
	v_mfma_f32_16x16x32_bf16 v[0:3], v[0:3], v[14:17], 0
	s_waitcnt lgkmcnt(4)
	v_mfma_f32_16x16x32_bf16 v[0:3], v[176:179], v[180:183], v[0:3]
	s_waitcnt lgkmcnt(2)
	v_mfma_f32_16x16x32_bf16 v[0:3], v[186:189], v[190:193], v[0:3]
	ds_read_b32 v10, v8
	s_waitcnt lgkmcnt(1)
	v_mfma_f32_16x16x32_bf16 v[0:3], v[194:197], v[198:201], v[0:3]
	v_mov_b32_e32 v14, 0
	v_mov_b32_e32 v15, 0
	s_and_saveexec_b64 s[0:1], vcc
	s_cbranch_execz .LBB0_286
	v_lshl_add_u32 v15, v7, 2, 0
	v_add_u32_e32 v15, 0x1a500, v15
	ds_read_b32 v15, v15
	s_waitcnt lgkmcnt(0)
	v_sub_f32_e32 v15, v10, v15
	v_mul_f32_e32 v15, 0x3fb8aa3b, v15
	v_exp_f32_e32 v15, v15
	s_nop 0
	v_mul_f32_e32 v15, v0, v15

; #define LAS __attribute__((address_space(3)))
; __device__ __forceinline__ f32x4 mfma16(const bf16x8& a, const bf16x8& b, const f32x4& c) { return __builtin_amdgcn_mfma_f32_16x16x32_bf16(a, b, c, 0, 0, 0); }
; __device__ __forceinline__ void dn_prep(const Params& p, LAS unsigned char* lds) {
;     ...
;                 if (sel == 0) {
;                     if (tj <= ti) {
;                         f32x4 acc = {0.f, 0.f, 0.f, 0.f};
; #pragma unroll
;                         for (int kk = 0; kk < 4; ++kk) { const bf16x8 a = *(const LAS bf16x8*)(Ks + (16 * ti + fr) * 136 + kk * 32 + 8 * fq), bb = *(const LAS bf16x8*)(Ks + (16 * tj + fr) * 136 + kk * 32 + 8 * fq); acc = mfma16(a, bb, acc); }
;                         const int j = 16 * tj + fr; const float Gj = G_s[j];
; #pragma unroll
;                         for (int jj = 0; jj < 4; ++jj) { const int i = 16 * ti + 4 * fq + jj;
;                             As[i * 68 + j] = (i > j) ? beta_s[i] * acc[jj] * __expf(G_s[i] - Gj) : 0.f; }
.LBB0_293:
	s_or_saveexec_b64 s[24:25], s[24:25]
	v_or_b32_e32 v0, v12, v156
	v_mad_u32_u24 v14, v0, s10, v11
	s_waitcnt lgkmcnt(0)
	v_or_b32_e32 v10, v7, v156
	s_xor_b64 exec, exec, s[24:25]
	s_cbranch_execz .LBB0_328
	ds_read_b128 v[0:3], v14 offset:17408
	v_add_u32_e32 v15, v11, v13
	ds_read_b128 v[16:19], v15 offset:17408
	v_cmp_gt_u32_e32 vcc, v10, v12
	ds_read_b128 v[176:179], v14 offset:17472
	ds_read_b128 v[180:183], v15 offset:17472
	ds_read_b128 v[186:189], v14 offset:17536
	ds_read_b128 v[190:193], v15 offset:17536
	ds_read_b128 v[194:197], v14 offset:17600
	ds_read_b128 v[198:201], v15 offset:17600
	s_waitcnt lgkmcnt(6)
	v_mfma_f32_16x16x32_bf16 v[0:3], v[0:3], v[16:19], 0
	s_waitcnt lgkmcnt(4)
	v_mfma_f32_16x16x32_bf16 v[0:3], v[176:179], v[180:183], v[0:3]
	s_waitcnt lgkmcnt(2)
	v_mfma_f32_16x16x32_bf16 v[0:3], v[186:189], v[190:193], v[0:3]
	v_lshl_add_u32 v15, v12, 2, 0
	v_add_u32_e32 v15, 0x1a500, v15
	ds_read_b32 v15, v15
	s_waitcnt lgkmcnt(1)
	v_mfma_f32_16x16x32_bf16 v[0:3], v[194:197], v[198:201], v[0:3]
	v_mov_b32_e32 v16, 0
	v_mov_b32_e32 v17, 0
	s_and_saveexec_b64 s[0:1], vcc
	s_cbranch_execz .LBB0_296
	v_lshl_add_u32 v17, v10, 2, 0
	v_add_u32_e32 v18, 0x1a500, v17
	ds_read_b32 v18, v18
	v_add_u32_e32 v17, 0x1a400, v17
	ds_read_b32 v17, v17
	s_waitcnt lgkmcnt(1)
	v_sub_f32_e32 v18, v18, v15
	v_mul_f32_e32 v18, 0x3fb8aa3b, v18
	v_exp_f32_e32 v18, v18
	s_waitcnt lgkmcnt(0)
	v_mul_f32_e32 v0, v0, v17
	v_mul_f32_e32 v17, v0, v18

; #define LAS __attribute__((address_space(3)))
; __device__ __forceinline__ f32x4 mfma16(const bf16x8& a, const bf16x8& b, const f32x4& c) { return __builtin_amdgcn_mfma_f32_16x16x32_bf16(a, b, c, 0, 0, 0); }
; __device__ __forceinline__ void dn_prep(const Params& p, LAS unsigned char* lds) {
;     ...
;                 if (sel == 0) {
;                     if (tj <= ti) {
;                         f32x4 acc = {0.f, 0.f, 0.f, 0.f};
; #pragma unroll
;                         for (int kk = 0; kk < 4; ++kk) { const bf16x8 a = *(const LAS bf16x8*)(Ks + (16 * ti + fr) * 136 + kk * 32 + 8 * fq), bb = *(const LAS bf16x8*)(Ks + (16 * tj + fr) * 136 + kk * 32 + 8 * fq); acc = mfma16(a, bb, acc); }
;                         const int j = 16 * tj + fr; const float Gj = G_s[j];
; #pragma unroll
;                         for (int jj = 0; jj < 4; ++jj) { const int i = 16 * ti + 4 * fq + jj;
;                             As[i * 68 + j] = (i > j) ? beta_s[i] * acc[jj] * __expf(G_s[i] - Gj) : 0.f; }
.LBB0_304:
	s_mov_b64 s[28:29], exec
	v_readlane_b32 s0, v248, 24
	v_readlane_b32 s1, v248, 25
	s_and_b64 s[0:1], s[28:29], s[0:1]
	s_mov_b64 exec, s[0:1]
	s_cbranch_execz .LBB0_314
	s_waitcnt lgkmcnt(4)
	v_or_b32_e32 v15, 16, v12
	v_mad_u32_u24 v24, v15, s10, v11
	ds_read_b128 v[0:3], v14 offset:17408
	s_waitcnt lgkmcnt(1)
	ds_read_b128 v[16:19], v24 offset:17408
	v_cmp_gt_u32_e32 vcc, v10, v15
	ds_read_b128 v[176:179], v14 offset:17472
	ds_read_b128 v[180:183], v24 offset:17472
	ds_read_b128 v[186:189], v14 offset:17536
	ds_read_b128 v[190:193], v24 offset:17536
	ds_read_b128 v[194:197], v14 offset:17600
	ds_read_b128 v[198:201], v24 offset:17600
	s_waitcnt lgkmcnt(6)
	v_mfma_f32_16x16x32_bf16 v[0:3], v[0:3], v[16:19], 0
	s_waitcnt lgkmcnt(4)
	v_mfma_f32_16x16x32_bf16 v[0:3], v[176:179], v[180:183], v[0:3]
	s_waitcnt lgkmcnt(2)
	v_mfma_f32_16x16x32_bf16 v[0:3], v[186:189], v[190:193], v[0:3]
	s_waitcnt lgkmcnt(0)
	v_mfma_f32_16x16x32_bf16 v[0:3], v[194:197], v[198:201], v[0:3]
	v_lshl_add_u32 v16, v15, 2, 0
	v_add_u32_e32 v16, 0x1a500, v16
	ds_read_b32 v16, v16
	v_mov_b32_e32 v17, 0
	v_mov_b32_e32 v19, 0
	s_and_saveexec_b64 s[0:1], vcc
	s_cbranch_execz .LBB0_307
	v_lshl_add_u32 v18, v10, 2, 0
	v_add_u32_e32 v19, 0x1a500, v18
	ds_read_b32 v19, v19
	v_add_u32_e32 v18, 0x1a400, v18
	ds_read_b32 v18, v18
	s_waitcnt lgkmcnt(1)
	v_sub_f32_e32 v19, v19, v16
	v_mul_f32_e32 v19, 0x3fb8aa3b, v19
	v_exp_f32_e32 v19, v19
	s_waitcnt lgkmcnt(0)
	v_mul_f32_e32 v0, v0, v18
	v_mul_f32_e32 v19, v0, v19

; #define LAS __attribute__((address_space(3)))
; __device__ __forceinline__ f32x4 mfma16(const bf16x8& a, const bf16x8& b, const f32x4& c) { return __builtin_amdgcn_mfma_f32_16x16x32_bf16(a, b, c, 0, 0, 0); }
; __device__ __forceinline__ void dn_prep(const Params& p, LAS unsigned char* lds) {
;     ...
;                 if (sel == 0) {
;                     if (tj <= ti) {
;                         f32x4 acc = {0.f, 0.f, 0.f, 0.f};
; #pragma unroll
;                         for (int kk = 0; kk < 4; ++kk) { const bf16x8 a = *(const LAS bf16x8*)(Ks + (16 * ti + fr) * 136 + kk * 32 + 8 * fq), bb = *(const LAS bf16x8*)(Ks + (16 * tj + fr) * 136 + kk * 32 + 8 * fq); acc = mfma16(a, bb, acc); }
;                         const int j = 16 * tj + fr; const float Gj = G_s[j];
; #pragma unroll
;                         for (int jj = 0; jj < 4; ++jj) { const int i = 16 * ti + 4 * fq + jj;
;                             As[i * 68 + j] = (i > j) ? beta_s[i] * acc[jj] * __expf(G_s[i] - Gj) : 0.f; }
.LBB0_316:
	s_and_saveexec_b64 s[28:29], s[20:21]
	s_cbranch_execz .LBB0_326
	s_waitcnt lgkmcnt(4)
	v_or_b32_e32 v15, 32, v12
	v_mad_u32_u24 v24, v15, s10, v11
	ds_read_b128 v[0:3], v14 offset:17408
	s_waitcnt lgkmcnt(1)
	ds_read_b128 v[16:19], v24 offset:17408
	v_cmp_gt_u32_e32 vcc, v10, v15
	ds_read_b128 v[176:179], v14 offset:17472
	ds_read_b128 v[180:183], v24 offset:17472
	ds_read_b128 v[186:189], v14 offset:17536
	ds_read_b128 v[190:193], v24 offset:17536
	ds_read_b128 v[194:197], v14 offset:17600
	ds_read_b128 v[198:201], v24 offset:17600
	s_waitcnt lgkmcnt(6)
	v_mfma_f32_16x16x32_bf16 v[0:3], v[0:3], v[16:19], 0
	s_waitcnt lgkmcnt(4)
	v_mfma_f32_16x16x32_bf16 v[0:3], v[176:179], v[180:183], v[0:3]
	s_waitcnt lgkmcnt(2)
	v_mfma_f32_16x16x32_bf16 v[0:3], v[186:189], v[190:193], v[0:3]
	s_waitcnt lgkmcnt(0)
	v_mfma_f32_16x16x32_bf16 v[0:3], v[194:197], v[198:201], v[0:3]
	v_lshl_add_u32 v16, v15, 2, 0
	v_add_u32_e32 v16, 0x1a500, v16
	ds_read_b32 v16, v16
	v_mov_b32_e32 v17, 0
	v_mov_b32_e32 v19, 0
	s_and_saveexec_b64 s[0:1], vcc
	s_cbranch_execz .LBB0_319
	v_lshl_add_u32 v18, v10, 2, 0
	v_add_u32_e32 v19, 0x1a500, v18
	ds_read_b32 v19, v19
	v_add_u32_e32 v18, 0x1a400, v18
	ds_read_b32 v18, v18
	s_waitcnt lgkmcnt(1)
	v_sub_f32_e32 v19, v19, v16
	v_mul_f32_e32 v19, 0x3fb8aa3b, v19
	v_exp_f32_e32 v19, v19
	s_waitcnt lgkmcnt(0)
	v_mul_f32_e32 v0, v0, v18
	v_mul_f32_e32 v19, v0, v19

; #define LAS __attribute__((address_space(3)))
; __device__ __forceinline__ f32x4 mfma16(const bf16x8& a, const bf16x8& b, const f32x4& c) { return __builtin_amdgcn_mfma_f32_16x16x32_bf16(a, b, c, 0, 0, 0); }
; __device__ __forceinline__ void dn_prep(const Params& p, LAS unsigned char* lds) {
;     ...
;                 } else {
;                     f32x4 acc = {0.f, 0.f, 0.f, 0.f};
;                     if (tj <= ti) {
; #pragma unroll
;                         for (int kk = 0; kk < 4; ++kk) { const bf16x8 a = *(const LAS bf16x8*)(Ks + (16 * tj + fr) * 136 + kk * 32 + 8 * fq), bb = *(const LAS bf16x8*)(Qs + (16 * ti + fr) * 136 + kk * 32 + 8 * fq); acc = mfma16(a, bb, acc); }
;                     }
;                     const int i = 16 * ti + fr; const float Gi = G_s[i];
;                     float v[4];
; #pragma unroll
;                     for (int jj = 0; jj < 4; ++jj) { const int j = 16 * tj + 4 * fq + jj; v[jj] = (i >= j) ? acc[jj] * __expf(Gi - G_s[j]) : 0.f; }
.LBB0_329:
	s_waitcnt lgkmcnt(4)
	v_mov_b32_e32 v15, 0
	v_mov_b32_e32 v0, 0
	v_mov_b32_e32 v1, 0
	v_mov_b32_e32 v2, 0
	v_mov_b32_e32 v3, 0
	s_mov_b64 s[28:29], exec
	v_readlane_b32 s0, v248, 24
	v_readlane_b32 s1, v248, 25
	s_and_b64 s[0:1], s[28:29], s[0:1]
	s_mov_b64 exec, s[0:1]
	s_cbranch_execz .LBB0_331
	v_add_u32_e32 v24, v11, v13
	ds_read_b128 v[0:3], v24 offset:21760
	ds_read_b128 v[16:19], v9
	ds_read_b128 v[176:179], v24 offset:21824
	ds_read_b128 v[180:183], v9 offset:64
	ds_read_b128 v[186:189], v24 offset:21888
	ds_read_b128 v[190:193], v9 offset:128
	ds_read_b128 v[194:197], v24 offset:21952
	ds_read_b128 v[198:201], v9 offset:192
	s_waitcnt lgkmcnt(6)
	v_mfma_f32_16x16x32_bf16 v[0:3], v[0:3], v[16:19], 0
	s_waitcnt lgkmcnt(4)
	v_mfma_f32_16x16x32_bf16 v[0:3], v[176:179], v[180:183], v[0:3]
	s_waitcnt lgkmcnt(2)
	v_mfma_f32_16x16x32_bf16 v[0:3], v[186:189], v[190:193], v[0:3]
	s_waitcnt lgkmcnt(0)
	v_mfma_f32_16x16x32_bf16 v[0:3], v[194:197], v[198:201], v[0:3]

; #define LAS __attribute__((address_space(3)))
; __device__ __forceinline__ f32x4 mfma16(const bf16x8& a, const bf16x8& b, const f32x4& c) { return __builtin_amdgcn_mfma_f32_16x16x32_bf16(a, b, c, 0, 0, 0); }
; __device__ __forceinline__ void dn_prep(const Params& p, LAS unsigned char* lds) {
;     ...
;                 } else {
;                     f32x4 acc = {0.f, 0.f, 0.f, 0.f};
;                     if (tj <= ti) {
; #pragma unroll
;                         for (int kk = 0; kk < 4; ++kk) { const bf16x8 a = *(const LAS bf16x8*)(Ks + (16 * tj + fr) * 136 + kk * 32 + 8 * fq), bb = *(const LAS bf16x8*)(Qs + (16 * ti + fr) * 136 + kk * 32 + 8 * fq); acc = mfma16(a, bb, acc); }
;                     }
;                     const int i = 16 * ti + fr; const float Gi = G_s[i];
;                     float v[4];
; #pragma unroll
;                     for (int jj = 0; jj < 4; ++jj) { const int j = 16 * tj + 4 * fq + jj; v[jj] = (i >= j) ? acc[jj] * __expf(Gi - G_s[j]) : 0.f; }
.LBB0_341:
	s_waitcnt lgkmcnt(4)
	v_mov_b32_e32 v15, 0
	v_mov_b32_e32 v0, 0
	v_mov_b32_e32 v1, 0
	v_mov_b32_e32 v2, 0
	v_mov_b32_e32 v3, 0
	s_and_saveexec_b64 s[28:29], s[20:21]
	s_cbranch_execz .LBB0_343
	v_add_u32_e32 v24, v11, v13
	ds_read_b128 v[0:3], v24 offset:26112
	s_waitcnt lgkmcnt(1)
	ds_read_b128 v[16:19], v9
	ds_read_b128 v[176:179], v24 offset:26176
	ds_read_b128 v[180:183], v9 offset:64
	ds_read_b128 v[186:189], v24 offset:26240
	ds_read_b128 v[190:193], v9 offset:128
	ds_read_b128 v[194:197], v24 offset:26304
	ds_read_b128 v[198:201], v9 offset:192
	s_waitcnt lgkmcnt(6)
	v_mfma_f32_16x16x32_bf16 v[0:3], v[0:3], v[16:19], 0
	s_waitcnt lgkmcnt(4)
	v_mfma_f32_16x16x32_bf16 v[0:3], v[176:179], v[180:183], v[0:3]
	s_waitcnt lgkmcnt(2)
	v_mfma_f32_16x16x32_bf16 v[0:3], v[186:189], v[190:193], v[0:3]
	s_waitcnt lgkmcnt(0)
	v_mfma_f32_16x16x32_bf16 v[0:3], v[194:197], v[198:201], v[0:3]

; #define LAS __attribute__((address_space(3)))
; __device__ __forceinline__ f32x4 mfma16(const bf16x8& a, const bf16x8& b, const f32x4& c) { return __builtin_amdgcn_mfma_f32_16x16x32_bf16(a, b, c, 0, 0, 0); }
; __device__ __forceinline__ void dn_prep(const Params& p, LAS unsigned char* lds) {
;     ...
;                 } else {
;                     f32x4 acc = {0.f, 0.f, 0.f, 0.f};
;                     if (tj <= ti) {
; #pragma unroll
;                         for (int kk = 0; kk < 4; ++kk) { const bf16x8 a = *(const LAS bf16x8*)(Ks + (16 * tj + fr) * 136 + kk * 32 + 8 * fq), bb = *(const LAS bf16x8*)(Qs + (16 * ti + fr) * 136 + kk * 32 + 8 * fq); acc = mfma16(a, bb, acc); }
;                     }
;                     const int i = 16 * ti + fr; const float Gi = G_s[i];
;                     float v[4];
; #pragma unroll
;                     for (int jj = 0; jj < 4; ++jj) { const int j = 16 * tj + 4 * fq + jj; v[jj] = (i >= j) ? acc[jj] * __expf(Gi - G_s[j]) : 0.f; }
.LBB0_353:
	v_mov_b32_e32 v10, 0
	v_mov_b32_e32 v0, 0
	v_mov_b32_e32 v1, 0
	v_mov_b32_e32 v2, 0
	v_mov_b32_e32 v3, 0
	s_and_saveexec_b64 s[28:29], s[22:23]
	s_cbranch_execz .LBB0_355
	v_add_u32_e32 v11, v11, v13
	ds_read_b128 v[0:3], v11 offset:30464
	s_waitcnt lgkmcnt(5)
	ds_read_b128 v[12:15], v9
	ds_read_b128 v[176:179], v11 offset:30528
	ds_read_b128 v[180:183], v9 offset:64
	ds_read_b128 v[186:189], v11 offset:30592
	ds_read_b128 v[190:193], v9 offset:128
	ds_read_b128 v[194:197], v11 offset:30656
	ds_read_b128 v[198:201], v9 offset:192
	s_waitcnt lgkmcnt(6)
	v_mfma_f32_16x16x32_bf16 v[0:3], v[0:3], v[12:15], 0
	s_waitcnt lgkmcnt(4)
	v_mfma_f32_16x16x32_bf16 v[0:3], v[176:179], v[180:183], v[0:3]
	s_waitcnt lgkmcnt(2)
	v_mfma_f32_16x16x32_bf16 v[0:3], v[186:189], v[190:193], v[0:3]
	s_waitcnt lgkmcnt(0)
	v_mfma_f32_16x16x32_bf16 v[0:3], v[194:197], v[198:201], v[0:3]

; #define LAS __attribute__((address_space(3)))
; __device__ __forceinline__ f32x4 mfma16(const bf16x8& a, const bf16x8& b, const f32x4& c) { return __builtin_amdgcn_mfma_f32_16x16x32_bf16(a, b, c, 0, 0, 0); }
; __device__ __forceinline__ void dn_prep(const Params& p, LAS unsigned char* lds) {
;     ...
;                 if (sel == 0) {
;                     if (tj <= ti) {
;                         f32x4 acc = {0.f, 0.f, 0.f, 0.f};
; #pragma unroll
;                         for (int kk = 0; kk < 4; ++kk) { const bf16x8 a = *(const LAS bf16x8*)(Ks + (16 * ti + fr) * 136 + kk * 32 + 8 * fq), bb = *(const LAS bf16x8*)(Ks + (16 * tj + fr) * 136 + kk * 32 + 8 * fq); acc = mfma16(a, bb, acc); }
;                         const int j = 16 * tj + fr; const float Gj = G_s[j];
; #pragma unroll
;                         for (int jj = 0; jj < 4; ++jj) { const int i = 16 * ti + 4 * fq + jj;
;                             As[i * 68 + j] = (i > j) ? beta_s[i] * acc[jj] * __expf(G_s[i] - Gj) : 0.f; }
.LBB0_364:
	s_and_saveexec_b64 s[28:29], s[22:23]
	s_cbranch_execz .LBB0_374
	v_or_b32_e32 v4, 48, v12
	v_mad_u32_u24 v5, v4, s10, v11
	ds_read_b128 v[0:3], v14 offset:17408
	s_waitcnt lgkmcnt(1)
	ds_read_b128 v[6:9], v5 offset:17408
	v_cmp_gt_u32_e32 vcc, v10, v4
	ds_read_b128 v[176:179], v14 offset:17472
	ds_read_b128 v[180:183], v5 offset:17472
	ds_read_b128 v[186:189], v14 offset:17536
	ds_read_b128 v[190:193], v5 offset:17536
	ds_read_b128 v[194:197], v14 offset:17600
	ds_read_b128 v[198:201], v5 offset:17600
	s_waitcnt lgkmcnt(6)
	v_mfma_f32_16x16x32_bf16 v[0:3], v[0:3], v[6:9], 0
	s_waitcnt lgkmcnt(4)
	v_mfma_f32_16x16x32_bf16 v[0:3], v[176:179], v[180:183], v[0:3]
	s_waitcnt lgkmcnt(2)
	v_mfma_f32_16x16x32_bf16 v[0:3], v[186:189], v[190:193], v[0:3]
	v_lshl_add_u32 v5, v4, 2, 0
	v_add_u32_e32 v5, 0x1a500, v5
	ds_read_b32 v5, v5
	s_waitcnt lgkmcnt(1)
	v_mfma_f32_16x16x32_bf16 v[0:3], v[194:197], v[198:201], v[0:3]
	v_mov_b32_e32 v6, 0
	v_lshl_add_u32 v7, v10, 2, 0
	v_mov_b32_e32 v9, 0
	s_and_saveexec_b64 s[0:1], vcc
	s_cbranch_execz .LBB0_367
	v_add_u32_e32 v8, 0x1a400, v7
	ds_read_b32 v8, v8
	s_waitcnt lgkmcnt(0)
	v_mul_f32_e32 v0, v0, v8
	v_add_u32_e32 v8, 0x1a500, v7
	ds_read_b32 v8, v8
	s_waitcnt lgkmcnt(0)
	v_sub_f32_e32 v8, v8, v5
	v_mul_f32_e32 v8, 0x3fb8aa3b, v8
	v_exp_f32_e32 v8, v8
	s_nop 0
	v_mul_f32_e32 v9, v0, v8
